# P8 (MLP up) output stores marked nt: the 256 MB hidden activation is not re-read until P9 and should not displace the GEMM operands in the last-level cache
# speedup vs baseline: 1.0100x; 1.0100x over previous
; __device__ __forceinline__ unsigned cvt_pk_bf16(float lo, float hi) { unsigned r; asm volatile("v_cvt_pk_bf16_f32 %0, %1, %2" : "=v"(r) : "v"(lo), "v"(hi)); return r; }
;     __device__ __forceinline__ void operator()(f32x4 (&acc)[2][2][4][2], const Unit& u, int wr, int wc, int fr, int fq) const {
;         int t2_ = threadIdx.x; asm volatile("" : "+v"(t2_)); (void)wr; (void)wc; (void)fr; (void)fq;
;         const int row0 = u.pm * BM + ((t2_ >> 8) & 1) * 64 + (t2_ & 15), col0 = u.pn * BM + ((t2_ >> 6) & 3) * 32 + 8 * ((t2_ >> 4) & 3);
; #pragma unroll
;         for (int ai = 0; ai < 2; ++ai)
; #pragma unroll
;             for (int m = 0; m < 4; ++m) {
;                 bf16_t* rowp = O + (size_t)(row0 + ai * HALF + m * 16) * ldc + col0;
; #pragma unroll
;                 for (int bj = 0; bj < 2; ++bj) {
;                     f32x4 v0 = acc[ai][bj][m][0], v1 = acc[ai][bj][m][1];
;                     f(v0, v1, u.pn, col0 + bj * HALF);
;                     u32x4 w; w.x = cvt_pk_bf16(v0[0], v0[1]); w.y = cvt_pk_bf16(v0[2], v0[3]); w.z = cvt_pk_bf16(v1[0], v1[1]); w.w = cvt_pk_bf16(v1[2], v1[3]);
;                     *(u32x4*)(rowp + bj * HALF) = w;
;                 }
;             }
.LBB0_1093:
	v_mov_b32_e32 v143, v210
	s_lshl_b32 s12, s81, 8
	v_lshrrev_b32_e32 v142, 2, v143
	v_and_b32_e32 v142, 64, v142
	v_and_b32_e32 v144, 15, v143
	v_lshrrev_b32_e32 v143, 1, v143
	v_or3_b32 v142, v142, s12, v144
	v_and_b32_e32 v143, 0x78, v143
	v_max_f32_e32 v122, v122, v122
	v_lshl_or_b32 v144, s80, 8, v143
	v_ashrrev_i32_e32 v143, 31, v142
	v_max_f32_e32 v122, 0, v122
	v_max_f32_e32 v123, v123, v123
	v_max_f32_e32 v124, v124, v124
	v_lshlrev_b64 v[148:149], 14, v[142:143]
	v_mul_f32_e32 v143, v122, v122
	v_max_f32_e32 v122, v127, v127
	v_max_f32_e32 v123, 0, v123
	v_max_f32_e32 v124, 0, v124
	v_ashrrev_i32_e32 v145, 31, v144
	v_max_f32_e32 v126, v126, v126
	v_max_f32_e32 v122, 0, v122
	v_mul_f32_e32 v127, v123, v123
	v_max_f32_e32 v123, v128, v128
	v_mul_f32_e32 v128, v124, v124
	v_max_f32_e32 v124, v129, v129
	v_max_f32_e32 v125, v125, v125
	v_lshl_add_u64 v[148:149], s[30:31], 0, v[148:149]
	v_lshlrev_b64 v[144:145], 1, v[144:145]
	v_max_f32_e32 v126, 0, v126
	v_mul_f32_e32 v122, v122, v122
	v_max_f32_e32 v123, 0, v123
	v_max_f32_e32 v124, 0, v124
	v_max_f32_e32 v125, 0, v125
	v_max_f32_e32 v114, v114, v114
	v_lshl_add_u64 v[148:149], v[148:149], 0, v[144:145]
	v_mul_f32_e32 v126, v126, v126
	v_mul_f32_e32 v123, v123, v123
	v_mul_f32_e32 v124, v124, v124
	v_mul_f32_e32 v125, v125, v125
	v_cvt_pk_bf16_f32 v122, v126, v122
	v_max_f32_e32 v114, 0, v114
	v_max_f32_e32 v115, v115, v115
	v_max_f32_e32 v116, v116, v116
	v_cvt_pk_bf16_f32 v123, v123, v124
	v_cvt_pk_bf16_f32 v124, v143, v127
	v_cvt_pk_bf16_f32 v125, v128, v125
	global_store_dwordx4 v[148:149], v[122:125], off nt
	v_max_f32_e32 v115, 0, v115
	v_max_f32_e32 v116, 0, v116
	v_mul_f32_e32 v122, v114, v114
	v_max_f32_e32 v114, v119, v119
	v_max_f32_e32 v118, v118, v118
	v_max_f32_e32 v114, 0, v114
	v_mul_f32_e32 v119, v115, v115
	v_max_f32_e32 v115, v120, v120
	v_mul_f32_e32 v120, v116, v116
	v_max_f32_e32 v116, v121, v121
	v_max_f32_e32 v117, v117, v117
	v_max_f32_e32 v118, 0, v118
	v_mul_f32_e32 v114, v114, v114
	v_max_f32_e32 v115, 0, v115
	v_max_f32_e32 v116, 0, v116
	v_max_f32_e32 v117, 0, v117
	v_mul_f32_e32 v118, v118, v118
	v_mul_f32_e32 v115, v115, v115
	v_mul_f32_e32 v116, v116, v116
	v_mul_f32_e32 v117, v117, v117
	v_cvt_pk_bf16_f32 v114, v118, v114
	v_max_f32_e32 v106, v106, v106
	v_cvt_pk_bf16_f32 v115, v115, v116
	v_cvt_pk_bf16_f32 v116, v122, v119
	v_cvt_pk_bf16_f32 v117, v120, v117
	global_store_dwordx4 v[148:149], v[114:117], off offset:256 nt
	v_max_f32_e32 v106, 0, v106
	v_max_f32_e32 v107, v107, v107
	v_or_b32_e32 v114, 16, v142
	v_max_f32_e32 v108, v108, v108
	v_ashrrev_i32_e32 v115, 31, v114
	v_mul_f32_e32 v116, v106, v106
	v_max_f32_e32 v106, v111, v111
	v_max_f32_e32 v107, 0, v107
	v_max_f32_e32 v108, 0, v108
	v_lshlrev_b64 v[114:115], 14, v[114:115]
	v_max_f32_e32 v110, v110, v110
	v_max_f32_e32 v106, 0, v106
	v_mul_f32_e32 v111, v107, v107
	v_max_f32_e32 v107, v112, v112
	v_mul_f32_e32 v112, v108, v108
	v_max_f32_e32 v108, v113, v113
	v_max_f32_e32 v109, v109, v109
	v_lshl_add_u64 v[114:115], s[30:31], 0, v[114:115]
	v_max_f32_e32 v110, 0, v110
	v_mul_f32_e32 v106, v106, v106
	v_max_f32_e32 v107, 0, v107
	v_max_f32_e32 v108, 0, v108
	v_max_f32_e32 v109, 0, v109
	v_max_f32_e32 v98, v98, v98
	v_lshl_add_u64 v[114:115], v[114:115], 0, v[144:145]
	v_mul_f32_e32 v110, v110, v110
	v_mul_f32_e32 v107, v107, v107
	v_mul_f32_e32 v108, v108, v108
	v_mul_f32_e32 v109, v109, v109
	v_cvt_pk_bf16_f32 v106, v110, v106
	v_max_f32_e32 v98, 0, v98
	v_max_f32_e32 v99, v99, v99
	v_max_f32_e32 v100, v100, v100
	v_cvt_pk_bf16_f32 v107, v107, v108
	v_cvt_pk_bf16_f32 v108, v116, v111
	v_cvt_pk_bf16_f32 v109, v112, v109
	global_store_dwordx4 v[114:115], v[106:109], off nt
	v_max_f32_e32 v99, 0, v99
	v_max_f32_e32 v100, 0, v100
	v_mul_f32_e32 v106, v98, v98
	v_max_f32_e32 v98, v103, v103
	v_max_f32_e32 v102, v102, v102
	v_max_f32_e32 v98, 0, v98
	v_mul_f32_e32 v103, v99, v99
	v_max_f32_e32 v99, v104, v104
	v_mul_f32_e32 v104, v100, v100
	v_max_f32_e32 v100, v105, v105
	v_max_f32_e32 v101, v101, v101
	v_max_f32_e32 v102, 0, v102
	v_mul_f32_e32 v98, v98, v98
	v_max_f32_e32 v99, 0, v99
	v_max_f32_e32 v100, 0, v100
	v_max_f32_e32 v101, 0, v101
	v_mul_f32_e32 v102, v102, v102
	v_mul_f32_e32 v99, v99, v99
	v_mul_f32_e32 v100, v100, v100
	v_mul_f32_e32 v101, v101, v101
	v_cvt_pk_bf16_f32 v98, v102, v98
	v_max_f32_e32 v90, v90, v90
	v_cvt_pk_bf16_f32 v99, v99, v100
	v_cvt_pk_bf16_f32 v100, v106, v103
	v_cvt_pk_bf16_f32 v101, v104, v101
	global_store_dwordx4 v[114:115], v[98:101], off offset:256 nt
	v_max_f32_e32 v90, 0, v90
	v_max_f32_e32 v91, v91, v91
	v_or_b32_e32 v98, 32, v142
	v_max_f32_e32 v92, v92, v92
	v_ashrrev_i32_e32 v99, 31, v98
	v_mul_f32_e32 v100, v90, v90
	v_max_f32_e32 v90, v95, v95
	v_max_f32_e32 v91, 0, v91
	v_max_f32_e32 v92, 0, v92
	v_lshlrev_b64 v[98:99], 14, v[98:99]
	v_max_f32_e32 v94, v94, v94
	v_max_f32_e32 v90, 0, v90
	v_mul_f32_e32 v95, v91, v91
	v_max_f32_e32 v91, v96, v96
	v_mul_f32_e32 v96, v92, v92
	v_max_f32_e32 v92, v97, v97
	v_max_f32_e32 v93, v93, v93
	v_lshl_add_u64 v[98:99], s[30:31], 0, v[98:99]
	v_max_f32_e32 v94, 0, v94
	v_mul_f32_e32 v90, v90, v90
	v_max_f32_e32 v91, 0, v91
	v_max_f32_e32 v92, 0, v92
	v_max_f32_e32 v93, 0, v93
	v_max_f32_e32 v82, v82, v82
	v_lshl_add_u64 v[98:99], v[98:99], 0, v[144:145]
	v_mul_f32_e32 v94, v94, v94
	v_mul_f32_e32 v91, v91, v91
	v_mul_f32_e32 v92, v92, v92
	v_mul_f32_e32 v93, v93, v93
	v_cvt_pk_bf16_f32 v90, v94, v90
	v_max_f32_e32 v82, 0, v82
	v_max_f32_e32 v83, v83, v83
	v_max_f32_e32 v84, v84, v84
	v_cvt_pk_bf16_f32 v91, v91, v92
	v_cvt_pk_bf16_f32 v92, v100, v95
	v_cvt_pk_bf16_f32 v93, v96, v93
; __device__ __forceinline__ unsigned cvt_pk_bf16(float lo, float hi) { unsigned r; asm volatile("v_cvt_pk_bf16_f32 %0, %1, %2" : "=v"(r) : "v"(lo), "v"(hi)); return r; }
;     __device__ __forceinline__ void operator()(f32x4 (&acc)[2][2][4][2], const Unit& u, int wr, int wc, int fr, int fq) const {
;     ...
;                 bf16_t* rowp = O + (size_t)(row0 + ai * HALF + m * 16) * ldc + col0;
; #pragma unroll
;                 for (int bj = 0; bj < 2; ++bj) {
;                     f32x4 v0 = acc[ai][bj][m][0], v1 = acc[ai][bj][m][1];
;                     f(v0, v1, u.pn, col0 + bj * HALF);
;                     u32x4 w; w.x = cvt_pk_bf16(v0[0], v0[1]); w.y = cvt_pk_bf16(v0[2], v0[3]); w.z = cvt_pk_bf16(v1[0], v1[1]); w.w = cvt_pk_bf16(v1[2], v1[3]);
;                     *(u32x4*)(rowp + bj * HALF) = w;
;                 }
	global_store_dwordx4 v[98:99], v[90:93], off nt
	v_max_f32_e32 v83, 0, v83
	v_max_f32_e32 v84, 0, v84
	v_mul_f32_e32 v90, v82, v82
	v_max_f32_e32 v82, v87, v87
	v_max_f32_e32 v86, v86, v86
	v_max_f32_e32 v82, 0, v82
	v_mul_f32_e32 v87, v83, v83
	v_max_f32_e32 v83, v88, v88
	v_mul_f32_e32 v88, v84, v84
	v_max_f32_e32 v84, v89, v89
	v_max_f32_e32 v85, v85, v85
	v_max_f32_e32 v86, 0, v86
	v_mul_f32_e32 v82, v82, v82
	v_max_f32_e32 v83, 0, v83
	v_max_f32_e32 v84, 0, v84
	v_max_f32_e32 v85, 0, v85
	v_mul_f32_e32 v86, v86, v86
	v_mul_f32_e32 v83, v83, v83
	v_mul_f32_e32 v84, v84, v84
	v_mul_f32_e32 v85, v85, v85
	v_cvt_pk_bf16_f32 v82, v86, v82
	v_max_f32_e32 v74, v74, v74
	v_cvt_pk_bf16_f32 v83, v83, v84
	v_cvt_pk_bf16_f32 v84, v90, v87
	v_cvt_pk_bf16_f32 v85, v88, v85
	global_store_dwordx4 v[98:99], v[82:85], off offset:256 nt
	v_max_f32_e32 v74, 0, v74
	v_max_f32_e32 v75, v75, v75
	v_or_b32_e32 v82, 48, v142
	v_max_f32_e32 v76, v76, v76
	v_ashrrev_i32_e32 v83, 31, v82
	v_mul_f32_e32 v84, v74, v74
	v_max_f32_e32 v74, v79, v79
	v_max_f32_e32 v75, 0, v75
	v_max_f32_e32 v76, 0, v76
	v_lshlrev_b64 v[82:83], 14, v[82:83]
	v_max_f32_e32 v78, v78, v78
	v_max_f32_e32 v74, 0, v74
	v_mul_f32_e32 v79, v75, v75
	v_max_f32_e32 v75, v80, v80
	v_mul_f32_e32 v80, v76, v76
	v_max_f32_e32 v76, v81, v81
	v_max_f32_e32 v77, v77, v77
	v_lshl_add_u64 v[82:83], s[30:31], 0, v[82:83]
	v_max_f32_e32 v78, 0, v78
	v_mul_f32_e32 v74, v74, v74
	v_max_f32_e32 v75, 0, v75
	v_max_f32_e32 v76, 0, v76
	v_max_f32_e32 v77, 0, v77
	v_max_f32_e32 v66, v66, v66
	v_lshl_add_u64 v[82:83], v[82:83], 0, v[144:145]
	v_mul_f32_e32 v78, v78, v78
	v_mul_f32_e32 v75, v75, v75
	v_mul_f32_e32 v76, v76, v76
	v_mul_f32_e32 v77, v77, v77
	v_cvt_pk_bf16_f32 v74, v78, v74
	v_max_f32_e32 v66, 0, v66
	v_max_f32_e32 v67, v67, v67
	v_max_f32_e32 v68, v68, v68
	v_cvt_pk_bf16_f32 v75, v75, v76
	v_cvt_pk_bf16_f32 v76, v84, v79
	v_cvt_pk_bf16_f32 v77, v80, v77
	global_store_dwordx4 v[82:83], v[74:77], off nt
	v_max_f32_e32 v67, 0, v67
	v_max_f32_e32 v68, 0, v68
	v_mul_f32_e32 v74, v66, v66
	v_max_f32_e32 v66, v71, v71
	v_max_f32_e32 v70, v70, v70
	v_max_f32_e32 v66, 0, v66
	v_mul_f32_e32 v71, v67, v67
	v_max_f32_e32 v67, v72, v72
	v_mul_f32_e32 v72, v68, v68
	v_max_f32_e32 v68, v73, v73
	v_max_f32_e32 v69, v69, v69
	v_max_f32_e32 v70, 0, v70
	v_mul_f32_e32 v66, v66, v66
	v_max_f32_e32 v67, 0, v67
	v_max_f32_e32 v68, 0, v68
	v_max_f32_e32 v69, 0, v69
	v_mul_f32_e32 v70, v70, v70
	v_mul_f32_e32 v67, v67, v67
	v_mul_f32_e32 v68, v68, v68
	v_mul_f32_e32 v69, v69, v69
	v_cvt_pk_bf16_f32 v66, v70, v66
	v_max_f32_e32 v58, v58, v58
	v_cvt_pk_bf16_f32 v67, v67, v68
	v_cvt_pk_bf16_f32 v68, v74, v71
	v_cvt_pk_bf16_f32 v69, v72, v69
	global_store_dwordx4 v[82:83], v[66:69], off offset:256 nt
	v_max_f32_e32 v58, 0, v58
	v_max_f32_e32 v59, v59, v59
	v_or_b32_e32 v66, 0x80, v142
	v_max_f32_e32 v60, v60, v60
	v_ashrrev_i32_e32 v67, 31, v66
	v_mul_f32_e32 v68, v58, v58
	v_max_f32_e32 v58, v63, v63
	v_max_f32_e32 v59, 0, v59
	v_max_f32_e32 v60, 0, v60
	v_lshlrev_b64 v[66:67], 14, v[66:67]
	v_max_f32_e32 v62, v62, v62
	v_max_f32_e32 v58, 0, v58
	v_mul_f32_e32 v63, v59, v59
	v_max_f32_e32 v59, v64, v64
	v_mul_f32_e32 v64, v60, v60
	v_max_f32_e32 v60, v65, v65
	v_max_f32_e32 v61, v61, v61
	v_lshl_add_u64 v[66:67], s[30:31], 0, v[66:67]
	v_max_f32_e32 v62, 0, v62
	v_mul_f32_e32 v58, v58, v58
	v_max_f32_e32 v59, 0, v59
	v_max_f32_e32 v60, 0, v60
	v_max_f32_e32 v61, 0, v61
	v_max_f32_e32 v50, v50, v50
	v_lshl_add_u64 v[66:67], v[66:67], 0, v[144:145]
	v_mul_f32_e32 v62, v62, v62
	v_mul_f32_e32 v59, v59, v59
	v_mul_f32_e32 v60, v60, v60
	v_mul_f32_e32 v61, v61, v61
	v_cvt_pk_bf16_f32 v58, v62, v58
	v_max_f32_e32 v50, 0, v50
	v_max_f32_e32 v51, v51, v51
	v_max_f32_e32 v52, v52, v52
	v_cvt_pk_bf16_f32 v59, v59, v60
	v_cvt_pk_bf16_f32 v60, v68, v63
	v_cvt_pk_bf16_f32 v61, v64, v61
	global_store_dwordx4 v[66:67], v[58:61], off nt
	v_max_f32_e32 v51, 0, v51
	v_max_f32_e32 v52, 0, v52
	v_mul_f32_e32 v58, v50, v50
	v_max_f32_e32 v50, v55, v55
	v_max_f32_e32 v54, v54, v54
	v_max_f32_e32 v50, 0, v50
	v_mul_f32_e32 v55, v51, v51
	v_max_f32_e32 v51, v56, v56
	v_mul_f32_e32 v56, v52, v52
	v_max_f32_e32 v52, v57, v57
	v_max_f32_e32 v53, v53, v53
	v_max_f32_e32 v54, 0, v54
	v_mul_f32_e32 v50, v50, v50
	v_max_f32_e32 v51, 0, v51
	v_max_f32_e32 v52, 0, v52
	v_max_f32_e32 v53, 0, v53
	v_mul_f32_e32 v54, v54, v54
	v_mul_f32_e32 v51, v51, v51
	v_mul_f32_e32 v52, v52, v52
	v_mul_f32_e32 v53, v53, v53
	v_cvt_pk_bf16_f32 v50, v54, v50
	v_max_f32_e32 v42, v42, v42
	v_cvt_pk_bf16_f32 v51, v51, v52
	v_cvt_pk_bf16_f32 v52, v58, v55
	v_cvt_pk_bf16_f32 v53, v56, v53
	global_store_dwordx4 v[66:67], v[50:53], off offset:256 nt
	v_max_f32_e32 v42, 0, v42
	v_max_f32_e32 v43, v43, v43
	v_or_b32_e32 v50, 0x90, v142
	v_max_f32_e32 v44, v44, v44
	v_ashrrev_i32_e32 v51, 31, v50
	v_mul_f32_e32 v52, v42, v42
	v_max_f32_e32 v42, v47, v47
	v_max_f32_e32 v43, 0, v43
	v_max_f32_e32 v44, 0, v44
	v_lshlrev_b64 v[50:51], 14, v[50:51]
	v_max_f32_e32 v46, v46, v46
	v_max_f32_e32 v42, 0, v42
	v_mul_f32_e32 v47, v43, v43
	v_max_f32_e32 v43, v48, v48
	v_mul_f32_e32 v48, v44, v44
	v_max_f32_e32 v44, v49, v49
	v_max_f32_e32 v45, v45, v45
	v_lshl_add_u64 v[50:51], s[30:31], 0, v[50:51]
	v_max_f32_e32 v46, 0, v46
; __device__ __forceinline__ unsigned cvt_pk_bf16(float lo, float hi) { unsigned r; asm volatile("v_cvt_pk_bf16_f32 %0, %1, %2" : "=v"(r) : "v"(lo), "v"(hi)); return r; }
;     __device__ __forceinline__ void operator()(f32x4 (&acc)[2][2][4][2], const Unit& u, int wr, int wc, int fr, int fq) const {
;     ...
;                 bf16_t* rowp = O + (size_t)(row0 + ai * HALF + m * 16) * ldc + col0;
; #pragma unroll
;                 for (int bj = 0; bj < 2; ++bj) {
;                     f32x4 v0 = acc[ai][bj][m][0], v1 = acc[ai][bj][m][1];
;                     f(v0, v1, u.pn, col0 + bj * HALF);
;                     u32x4 w; w.x = cvt_pk_bf16(v0[0], v0[1]); w.y = cvt_pk_bf16(v0[2], v0[3]); w.z = cvt_pk_bf16(v1[0], v1[1]); w.w = cvt_pk_bf16(v1[2], v1[3]);
;                     *(u32x4*)(rowp + bj * HALF) = w;
;                 }
	v_mul_f32_e32 v42, v42, v42
	v_max_f32_e32 v43, 0, v43
	v_max_f32_e32 v44, 0, v44
	v_max_f32_e32 v45, 0, v45
	v_max_f32_e32 v34, v34, v34
	v_lshl_add_u64 v[50:51], v[50:51], 0, v[144:145]
	v_mul_f32_e32 v46, v46, v46
	v_mul_f32_e32 v43, v43, v43
	v_mul_f32_e32 v44, v44, v44
	v_mul_f32_e32 v45, v45, v45
	v_cvt_pk_bf16_f32 v42, v46, v42
	v_max_f32_e32 v34, 0, v34
	v_max_f32_e32 v35, v35, v35
	v_max_f32_e32 v36, v36, v36
	v_cvt_pk_bf16_f32 v43, v43, v44
	v_cvt_pk_bf16_f32 v44, v52, v47
	v_cvt_pk_bf16_f32 v45, v48, v45
	global_store_dwordx4 v[50:51], v[42:45], off nt
	v_max_f32_e32 v35, 0, v35
	v_max_f32_e32 v36, 0, v36
	v_mul_f32_e32 v42, v34, v34
	v_max_f32_e32 v34, v39, v39
	v_max_f32_e32 v38, v38, v38
	v_max_f32_e32 v34, 0, v34
	v_mul_f32_e32 v39, v35, v35
	v_max_f32_e32 v35, v40, v40
	v_mul_f32_e32 v40, v36, v36
	v_max_f32_e32 v36, v41, v41
	v_max_f32_e32 v37, v37, v37
	v_max_f32_e32 v38, 0, v38
	v_mul_f32_e32 v34, v34, v34
	v_max_f32_e32 v35, 0, v35
	v_max_f32_e32 v36, 0, v36
	v_max_f32_e32 v37, 0, v37
	v_mul_f32_e32 v38, v38, v38
	v_mul_f32_e32 v35, v35, v35
	v_mul_f32_e32 v36, v36, v36
	v_mul_f32_e32 v37, v37, v37
	v_cvt_pk_bf16_f32 v34, v38, v34
	v_max_f32_e32 v26, v26, v26
	v_cvt_pk_bf16_f32 v35, v35, v36
	v_cvt_pk_bf16_f32 v36, v42, v39
	v_cvt_pk_bf16_f32 v37, v40, v37
	global_store_dwordx4 v[50:51], v[34:37], off offset:256 nt
	v_max_f32_e32 v26, 0, v26
	v_max_f32_e32 v27, v27, v27
	v_or_b32_e32 v34, 0xa0, v142
	v_max_f32_e32 v28, v28, v28
	v_ashrrev_i32_e32 v35, 31, v34
	v_mul_f32_e32 v36, v26, v26
	v_max_f32_e32 v26, v31, v31
	v_max_f32_e32 v27, 0, v27
	v_max_f32_e32 v28, 0, v28
	v_lshlrev_b64 v[34:35], 14, v[34:35]
	v_max_f32_e32 v30, v30, v30
	v_max_f32_e32 v26, 0, v26
	v_mul_f32_e32 v31, v27, v27
	v_max_f32_e32 v27, v32, v32
	v_mul_f32_e32 v32, v28, v28
	v_max_f32_e32 v28, v33, v33
	v_max_f32_e32 v29, v29, v29
	v_lshl_add_u64 v[34:35], s[30:31], 0, v[34:35]
	v_max_f32_e32 v30, 0, v30
	v_mul_f32_e32 v26, v26, v26
	v_max_f32_e32 v27, 0, v27
	v_max_f32_e32 v28, 0, v28
	v_max_f32_e32 v29, 0, v29
	v_max_f32_e32 v18, v18, v18
	v_lshl_add_u64 v[34:35], v[34:35], 0, v[144:145]
	v_mul_f32_e32 v30, v30, v30
	v_mul_f32_e32 v27, v27, v27
	v_mul_f32_e32 v28, v28, v28
	v_mul_f32_e32 v29, v29, v29
	v_cvt_pk_bf16_f32 v26, v30, v26
	v_max_f32_e32 v18, 0, v18
	v_max_f32_e32 v19, v19, v19
	v_max_f32_e32 v20, v20, v20
	v_cvt_pk_bf16_f32 v27, v27, v28
	v_cvt_pk_bf16_f32 v28, v36, v31
	v_cvt_pk_bf16_f32 v29, v32, v29
	global_store_dwordx4 v[34:35], v[26:29], off nt
	v_max_f32_e32 v19, 0, v19
	v_max_f32_e32 v20, 0, v20
	v_mul_f32_e32 v26, v18, v18
	v_max_f32_e32 v18, v23, v23
	v_max_f32_e32 v22, v22, v22
	v_max_f32_e32 v18, 0, v18
	v_mul_f32_e32 v23, v19, v19
	v_max_f32_e32 v19, v24, v24
	v_mul_f32_e32 v24, v20, v20
	v_max_f32_e32 v20, v25, v25
	v_max_f32_e32 v21, v21, v21
	v_max_f32_e32 v22, 0, v22
	v_mul_f32_e32 v18, v18, v18
	v_max_f32_e32 v19, 0, v19
	v_max_f32_e32 v20, 0, v20
	v_max_f32_e32 v21, 0, v21
	v_mul_f32_e32 v22, v22, v22
	v_mul_f32_e32 v19, v19, v19
	v_mul_f32_e32 v20, v20, v20
	v_mul_f32_e32 v21, v21, v21
	v_cvt_pk_bf16_f32 v18, v22, v18
	v_max_f32_e32 v10, v10, v10
	v_cvt_pk_bf16_f32 v19, v19, v20
	v_cvt_pk_bf16_f32 v20, v26, v23
	v_cvt_pk_bf16_f32 v21, v24, v21
	global_store_dwordx4 v[34:35], v[18:21], off offset:256 nt
	v_max_f32_e32 v10, 0, v10
	v_max_f32_e32 v11, v11, v11
	v_or_b32_e32 v18, 0xb0, v142
	v_max_f32_e32 v12, v12, v12
	v_ashrrev_i32_e32 v19, 31, v18
	v_mul_f32_e32 v20, v10, v10
	v_max_f32_e32 v10, v15, v15
	v_max_f32_e32 v11, 0, v11
	v_max_f32_e32 v12, 0, v12
	v_lshlrev_b64 v[18:19], 14, v[18:19]
	v_max_f32_e32 v14, v14, v14
	v_max_f32_e32 v10, 0, v10
	v_mul_f32_e32 v15, v11, v11
	v_max_f32_e32 v11, v16, v16
	v_mul_f32_e32 v16, v12, v12
	v_max_f32_e32 v12, v17, v17
	v_max_f32_e32 v13, v13, v13
	v_lshl_add_u64 v[18:19], s[30:31], 0, v[18:19]
	v_max_f32_e32 v14, 0, v14
	v_mul_f32_e32 v10, v10, v10
	v_max_f32_e32 v11, 0, v11
	v_max_f32_e32 v12, 0, v12
	v_max_f32_e32 v13, 0, v13
	v_max_f32_e32 v2, v2, v2
	v_max_f32_e32 v3, v3, v3
	v_max_f32_e32 v4, v4, v4
	v_lshl_add_u64 v[18:19], v[18:19], 0, v[144:145]
	v_mul_f32_e32 v14, v14, v14
	v_mul_f32_e32 v11, v11, v11
	v_mul_f32_e32 v12, v12, v12
	v_mul_f32_e32 v13, v13, v13
	v_cvt_pk_bf16_f32 v10, v14, v10
	v_max_f32_e32 v2, 0, v2
	v_max_f32_e32 v3, 0, v3
	v_max_f32_e32 v4, 0, v4
	v_cvt_pk_bf16_f32 v11, v11, v12
	v_cvt_pk_bf16_f32 v12, v20, v15
	v_cvt_pk_bf16_f32 v13, v16, v13
	global_store_dwordx4 v[18:19], v[10:13], off nt
	v_max_f32_e32 v5, v5, v5
	v_max_f32_e32 v6, v6, v6
	v_mul_f32_e32 v10, v2, v2
	v_max_f32_e32 v2, v7, v7
	v_mul_f32_e32 v7, v3, v3
	v_max_f32_e32 v3, v8, v8
	v_mul_f32_e32 v8, v4, v4
	v_max_f32_e32 v4, v9, v9
	v_max_f32_e32 v2, 0, v2
	v_max_f32_e32 v3, 0, v3
	v_max_f32_e32 v4, 0, v4
	v_max_f32_e32 v5, 0, v5
	v_max_f32_e32 v6, 0, v6
	v_mul_f32_e32 v2, v2, v2
	v_mul_f32_e32 v3, v3, v3
	v_mul_f32_e32 v4, v4, v4
	v_mul_f32_e32 v5, v5, v5
	s_andn2_b64 vcc, exec, s[40:41]
	s_mov_b64 s[40:41], -1
	v_mul_f32_e32 v6, v6, v6
	v_cvt_pk_bf16_f32 v2, v6, v2
	v_cvt_pk_bf16_f32 v3, v3, v4
	v_cvt_pk_bf16_f32 v4, v10, v7
	v_cvt_pk_bf16_f32 v5, v8, v5
	global_store_dwordx4 v[18:19], v[2:5], off offset:256 nt
	s_cbranch_vccnz .LBB0_1082
	s_andn2_b64 vcc, exec, s[28:29]
	s_cbranch_vccnz .LBB0_1081
	s_barrier
	s_branch .LBB0_1081
